# v043_poolpipe16
# speedup vs baseline: 1.0346x; 1.0346x over previous
; __device__ __forceinline__ float bflo(unsigned u) { return __uint_as_float(u << 16); }
; __device__ __forceinline__ float bfhi(unsigned u) { return __uint_as_float(u & 0xffff0000u); }
; #define SCHED __builtin_amdgcn_sched_barrier(0)
; template <int W>
; __device__ __forceinline__ void pool_compute(const Params& p, int layer, int g, int dh, int tt, const int tidx) {
;     ...
;   for (int kb = 0; kb < 4; ++kb) {
;     u32x4 av[4][4];
; #pragma unroll
;     for (int k4 = 0; k4 < 4; ++k4)
; #pragma unroll
;       for (int d = 0; d < 4; ++d)
;         av[k4][d] = *reinterpret_cast<const u32x4*>(wpb + (woff + (unsigned)(((dh * 4 + d) * 32) * 512 + (kb * 4 + k4) * 32)));
;     SCHED;
; #pragma unroll
;     for (int k4 = 0; k4 < 4; ++k4) {
;       const int ks = kb * 4 + k4;
;       float sum[8];
; #pragma unroll
;       for (int j = 0; j < 8; ++j) sum[j] = 0.f;
;       u32x4 x0 = *reinterpret_cast<const u32x4*>(xl + ks * 32);
; #pragma unroll
;       for (int i = 0; i < W; ++i) {
;         u32x4 xv = *reinterpret_cast<const u32x4*>(xl + ks * 32 - i * PXS);
;         sum[0] += bflo(xv.x); sum[1] += bfhi(xv.x); sum[2] += bflo(xv.y); sum[3] += bfhi(xv.y);
;         sum[4] += bflo(xv.z); sum[5] += bfhi(xv.z); sum[6] += bflo(xv.w); sum[7] += bfhi(xv.w);
;       }
.LBB0_185:
	v_add_co_u32_e32 v68, vcc, s13, v136
	s_nop 1
	v_addc_co_u32_e32 v69, vcc, 0, v137, vcc
	v_add_co_u32_e32 v72, vcc, s14, v136
	s_nop 1
	v_addc_co_u32_e32 v73, vcc, 0, v137, vcc
	v_add_co_u32_e32 v76, vcc, s15, v136
	s_nop 1
	v_addc_co_u32_e32 v77, vcc, 0, v137, vcc
	global_load_dwordx4 v[114:117], v[136:137], off
	global_load_dwordx4 v[98:101], v[136:137], off offset:32
	global_load_dwordx4 v[118:121], v[68:69], off
	global_load_dwordx4 v[102:105], v[68:69], off offset:32
	global_load_dwordx4 v[122:125], v[72:73], off
	global_load_dwordx4 v[106:109], v[72:73], off offset:32
	global_load_dwordx4 v[126:129], v[76:77], off
	global_load_dwordx4 v[110:113], v[76:77], off offset:32
	global_load_dwordx4 v[80:83], v[136:137], off offset:64
	global_load_dwordx4 v[64:67], v[136:137], off offset:96
	global_load_dwordx4 v[84:87], v[68:69], off offset:64
	s_nop 0
	global_load_dwordx4 v[68:71], v[68:69], off offset:96
	s_nop 0
	global_load_dwordx4 v[88:91], v[72:73], off offset:64
	s_nop 0
	global_load_dwordx4 v[72:75], v[72:73], off offset:96
	s_nop 0
	global_load_dwordx4 v[92:95], v[76:77], off offset:64
	s_nop 0
	global_load_dwordx4 v[76:79], v[76:77], off offset:96
	v_add_u32_e32 v144, s12, v143
	v_add_u32_e32 v131, 0x141c0, v144
	ds_read_b128 v[150:153], v131
	v_add_u32_e32 v154, 0x13fb0, v144
	ds_read_b128 v[154:157], v154
	v_add_u32_e32 v130, 0x122d0, v144
	s_addk_i32 s12, 0x80
	s_waitcnt lgkmcnt(1)
	v_and_b32_e32 v146, 0xffff0000, v150
	v_add_f32_e32 v132, 0, v146
	v_lshlrev_b32_e32 v147, 16, v151
	s_waitcnt lgkmcnt(0)
	v_lshlrev_b32_e32 v165, 16, v154
	v_and_b32_e32 v154, 0xffff0000, v154
	v_add_f32_e32 v133, 0, v147
	v_and_b32_e32 v148, 0xffff0000, v151
	v_add_f32_e32 v132, v132, v154
	v_lshlrev_b32_e32 v154, 16, v155
	v_add_f32_e32 v158, 0, v148
	v_lshlrev_b32_e32 v149, 16, v152
	v_add_f32_e32 v133, v133, v154
	v_and_b32_e32 v154, 0xffff0000, v155
	v_lshlrev_b32_e32 v145, 16, v150
	v_add_f32_e32 v159, 0, v149
	v_and_b32_e32 v150, 0xffff0000, v152
	v_add_f32_e32 v158, v158, v154
	v_lshlrev_b32_e32 v154, 16, v156
	v_add_f32_e32 v160, 0, v150
	v_lshlrev_b32_e32 v151, 16, v153
	v_add_f32_e32 v159, v159, v154
	v_and_b32_e32 v154, 0xffff0000, v156
	v_add_f32_e32 v161, 0, v151
	v_and_b32_e32 v152, 0xffff0000, v153
	v_add_f32_e32 v160, v160, v154
	v_lshlrev_b32_e32 v154, 16, v157
	v_add_f32_e32 v153, 0, v152
	v_add_f32_e32 v161, v161, v154
	v_and_b32_e32 v154, 0xffff0000, v157
	v_add_f32_e32 v153, v153, v154
	v_add_u32_e32 v154, 0x13da0, v144
	ds_read_b128 v[154:157], v154
	v_add_f32_e32 v131, 0, v145
	v_add_f32_e32 v131, v131, v165
	v_lshl_add_u64 v[136:137], v[136:137], 0, s[16:17]
	s_cmpk_lg_i32 s12, 0x200
	s_waitcnt lgkmcnt(0)
	v_lshlrev_b32_e32 v165, 16, v154
	v_and_b32_e32 v154, 0xffff0000, v154
	v_add_f32_e32 v132, v132, v154
	v_lshlrev_b32_e32 v154, 16, v155
	v_add_f32_e32 v133, v133, v154
	v_and_b32_e32 v154, 0xffff0000, v155
	v_add_f32_e32 v158, v158, v154
	v_lshlrev_b32_e32 v154, 16, v156
	v_add_f32_e32 v159, v159, v154
	v_and_b32_e32 v154, 0xffff0000, v156
	v_add_f32_e32 v160, v160, v154
	v_lshlrev_b32_e32 v154, 16, v157
	v_add_f32_e32 v161, v161, v154
	v_and_b32_e32 v154, 0xffff0000, v157
	v_add_f32_e32 v153, v153, v154
	v_add_u32_e32 v168, 0x13b90, v144
	ds_read_b128 v[168:171], v168
	v_add_f32_e32 v131, v131, v165
	s_waitcnt lgkmcnt(0)
	v_add_u32_e32 v154, 0x13980, v144
	ds_read_b128 v[154:157], v154
	v_lshlrev_b32_e32 v165, 16, v168
	v_and_b32_e32 v168, 0xffff0000, v168
	v_add_f32_e32 v132, v132, v168
	v_lshlrev_b32_e32 v168, 16, v169
	v_add_f32_e32 v133, v133, v168
	v_and_b32_e32 v168, 0xffff0000, v169
	v_add_f32_e32 v158, v158, v168
	v_lshlrev_b32_e32 v168, 16, v170
	v_add_f32_e32 v159, v159, v168
	v_and_b32_e32 v168, 0xffff0000, v170
	v_add_f32_e32 v160, v160, v168
	v_lshlrev_b32_e32 v168, 16, v171
	v_add_f32_e32 v161, v161, v168
	v_and_b32_e32 v168, 0xffff0000, v171
	v_add_f32_e32 v153, v153, v168
	v_add_f32_e32 v131, v131, v165
	s_waitcnt lgkmcnt(0)
	v_add_u32_e32 v168, 0x13770, v144
	ds_read_b128 v[168:171], v168
	v_lshlrev_b32_e32 v165, 16, v154
	v_and_b32_e32 v154, 0xffff0000, v154
	v_add_f32_e32 v132, v132, v154
	v_lshlrev_b32_e32 v154, 16, v155
	v_add_f32_e32 v133, v133, v154
	v_and_b32_e32 v154, 0xffff0000, v155
	v_add_f32_e32 v158, v158, v154
	v_lshlrev_b32_e32 v154, 16, v156
	v_add_f32_e32 v159, v159, v154
	v_and_b32_e32 v154, 0xffff0000, v156
	v_add_f32_e32 v160, v160, v154
	v_lshlrev_b32_e32 v154, 16, v157
	v_add_f32_e32 v161, v161, v154
	v_and_b32_e32 v154, 0xffff0000, v157
	v_add_f32_e32 v153, v153, v154
	v_add_f32_e32 v131, v131, v165
	s_waitcnt lgkmcnt(0)
	v_add_u32_e32 v154, 0x13560, v144
	ds_read_b128 v[154:157], v154
	v_lshlrev_b32_e32 v165, 16, v168
	v_and_b32_e32 v168, 0xffff0000, v168
	v_add_f32_e32 v132, v132, v168
	v_lshlrev_b32_e32 v168, 16, v169
	v_add_f32_e32 v133, v133, v168
	v_and_b32_e32 v168, 0xffff0000, v169
	v_add_f32_e32 v158, v158, v168
	v_lshlrev_b32_e32 v168, 16, v170
	v_add_f32_e32 v159, v159, v168
	v_and_b32_e32 v168, 0xffff0000, v170
	v_add_f32_e32 v160, v160, v168
	v_lshlrev_b32_e32 v168, 16, v171
	v_add_f32_e32 v161, v161, v168
	v_and_b32_e32 v168, 0xffff0000, v171
	v_add_f32_e32 v153, v153, v168
	v_add_f32_e32 v131, v131, v165
	s_waitcnt lgkmcnt(0)
	v_add_u32_e32 v168, 0x13350, v144
	ds_read_b128 v[168:171], v168
	v_lshlrev_b32_e32 v165, 16, v154
	v_and_b32_e32 v154, 0xffff0000, v154
	v_add_f32_e32 v132, v132, v154
	v_lshlrev_b32_e32 v154, 16, v155
	v_add_f32_e32 v133, v133, v154
	v_and_b32_e32 v154, 0xffff0000, v155
	v_add_f32_e32 v158, v158, v154
	v_lshlrev_b32_e32 v154, 16, v156
	v_add_f32_e32 v159, v159, v154
	v_and_b32_e32 v154, 0xffff0000, v156
	v_add_f32_e32 v160, v160, v154
	v_lshlrev_b32_e32 v154, 16, v157
	v_add_f32_e32 v161, v161, v154
	v_and_b32_e32 v154, 0xffff0000, v157
	v_add_f32_e32 v153, v153, v154
	v_add_f32_e32 v131, v131, v165
	s_waitcnt lgkmcnt(0)
; __device__ __forceinline__ float bflo(unsigned u) { return __uint_as_float(u << 16); }
; __device__ __forceinline__ float bfhi(unsigned u) { return __uint_as_float(u & 0xffff0000u); }
; template <int W>
; __device__ __forceinline__ void pool_compute(const Params& p, int layer, int g, int dh, int tt, const int tidx) {
;     ...
;       u32x4 x0 = *reinterpret_cast<const u32x4*>(xl + ks * 32);
; #pragma unroll
;       for (int i = 0; i < W; ++i) {
;         u32x4 xv = *reinterpret_cast<const u32x4*>(xl + ks * 32 - i * PXS);
;         sum[0] += bflo(xv.x); sum[1] += bfhi(xv.x); sum[2] += bflo(xv.y); sum[3] += bfhi(xv.y);
;         sum[4] += bflo(xv.z); sum[5] += bfhi(xv.z); sum[6] += bflo(xv.w); sum[7] += bfhi(xv.w);
;       }
;       u32x4 bfr;
;       bfr.x = pack2(sum[0] * inv - bflo(x0.x), sum[1] * inv - bfhi(x0.x));
;       bfr.y = pack2(sum[2] * inv - bflo(x0.y), sum[3] * inv - bfhi(x0.y));
;       bfr.z = pack2(sum[4] * inv - bflo(x0.z), sum[5] * inv - bfhi(x0.z));
;       bfr.w = pack2(sum[6] * inv - bflo(x0.w), sum[7] * inv - bfhi(x0.w));
; #pragma unroll
;       for (int d = 0; d < 4; ++d) acc[d] = __builtin_amdgcn_mfma_f32_32x32x16_bf16(as_bf16x8(av[k4][d]), as_bf16x8(bfr), acc[d], 0, 0, 0);
	v_add_u32_e32 v154, 0x13140, v144
	ds_read_b128 v[154:157], v154
	v_lshlrev_b32_e32 v165, 16, v168
	v_and_b32_e32 v168, 0xffff0000, v168
	v_add_f32_e32 v132, v132, v168
	v_lshlrev_b32_e32 v168, 16, v169
	v_add_f32_e32 v133, v133, v168
	v_and_b32_e32 v168, 0xffff0000, v169
	v_add_f32_e32 v158, v158, v168
	v_lshlrev_b32_e32 v168, 16, v170
	v_add_f32_e32 v159, v159, v168
	v_and_b32_e32 v168, 0xffff0000, v170
	v_add_f32_e32 v160, v160, v168
	v_lshlrev_b32_e32 v168, 16, v171
	v_add_f32_e32 v161, v161, v168
	v_and_b32_e32 v168, 0xffff0000, v171
	v_add_f32_e32 v153, v153, v168
	v_add_f32_e32 v131, v131, v165
	s_waitcnt lgkmcnt(0)
	v_add_u32_e32 v168, 0x12f30, v144
	ds_read_b128 v[168:171], v168
	v_lshlrev_b32_e32 v165, 16, v154
	v_and_b32_e32 v154, 0xffff0000, v154
	v_add_f32_e32 v132, v132, v154
	v_lshlrev_b32_e32 v154, 16, v155
	v_add_f32_e32 v133, v133, v154
	v_and_b32_e32 v154, 0xffff0000, v155
	v_add_f32_e32 v158, v158, v154
	v_lshlrev_b32_e32 v154, 16, v156
	v_add_f32_e32 v159, v159, v154
	v_and_b32_e32 v154, 0xffff0000, v156
	v_add_f32_e32 v160, v160, v154
	v_lshlrev_b32_e32 v154, 16, v157
	v_add_f32_e32 v161, v161, v154
	v_and_b32_e32 v154, 0xffff0000, v157
	v_add_f32_e32 v153, v153, v154
	v_add_f32_e32 v131, v131, v165
	s_waitcnt lgkmcnt(0)
	v_add_u32_e32 v154, 0x12d20, v144
	ds_read_b128 v[154:157], v154
	v_lshlrev_b32_e32 v165, 16, v168
	v_and_b32_e32 v168, 0xffff0000, v168
	v_add_f32_e32 v132, v132, v168
	v_lshlrev_b32_e32 v168, 16, v169
	v_add_f32_e32 v133, v133, v168
	v_and_b32_e32 v168, 0xffff0000, v169
	v_add_f32_e32 v158, v158, v168
	v_lshlrev_b32_e32 v168, 16, v170
	v_add_f32_e32 v159, v159, v168
	v_and_b32_e32 v168, 0xffff0000, v170
	v_add_f32_e32 v160, v160, v168
	v_lshlrev_b32_e32 v168, 16, v171
	v_add_f32_e32 v161, v161, v168
	v_and_b32_e32 v168, 0xffff0000, v171
	v_add_f32_e32 v153, v153, v168
	v_add_f32_e32 v131, v131, v165
	s_waitcnt lgkmcnt(0)
	v_add_u32_e32 v168, 0x12b10, v144
	ds_read_b128 v[168:171], v168
	v_lshlrev_b32_e32 v165, 16, v154
	v_and_b32_e32 v154, 0xffff0000, v154
	v_add_f32_e32 v132, v132, v154
	v_lshlrev_b32_e32 v154, 16, v155
	v_add_f32_e32 v133, v133, v154
	v_and_b32_e32 v154, 0xffff0000, v155
	v_add_f32_e32 v158, v158, v154
	v_lshlrev_b32_e32 v154, 16, v156
	v_add_f32_e32 v159, v159, v154
	v_and_b32_e32 v154, 0xffff0000, v156
	v_add_f32_e32 v160, v160, v154
	v_lshlrev_b32_e32 v154, 16, v157
	v_add_f32_e32 v161, v161, v154
	v_and_b32_e32 v154, 0xffff0000, v157
	v_add_f32_e32 v153, v153, v154
	v_add_f32_e32 v131, v131, v165
	s_waitcnt lgkmcnt(0)
	v_add_u32_e32 v154, 0x12900, v144
	ds_read_b128 v[154:157], v154
	v_lshlrev_b32_e32 v165, 16, v168
	v_and_b32_e32 v168, 0xffff0000, v168
	v_add_f32_e32 v132, v132, v168
	v_lshlrev_b32_e32 v168, 16, v169
	v_add_f32_e32 v133, v133, v168
	v_and_b32_e32 v168, 0xffff0000, v169
	v_add_f32_e32 v158, v158, v168
	v_lshlrev_b32_e32 v168, 16, v170
	v_add_f32_e32 v159, v159, v168
	v_and_b32_e32 v168, 0xffff0000, v170
	v_add_f32_e32 v160, v160, v168
	v_lshlrev_b32_e32 v168, 16, v171
	v_add_f32_e32 v161, v161, v168
	v_and_b32_e32 v168, 0xffff0000, v171
	v_add_f32_e32 v153, v153, v168
	v_add_f32_e32 v131, v131, v165
	s_waitcnt lgkmcnt(0)
	v_add_u32_e32 v168, 0x126f0, v144
	ds_read_b128 v[168:171], v168
	v_lshlrev_b32_e32 v165, 16, v154
	v_and_b32_e32 v154, 0xffff0000, v154
	v_add_f32_e32 v132, v132, v154
	v_lshlrev_b32_e32 v154, 16, v155
	v_add_f32_e32 v133, v133, v154
	v_and_b32_e32 v154, 0xffff0000, v155
	v_add_f32_e32 v158, v158, v154
	v_lshlrev_b32_e32 v154, 16, v156
	v_add_f32_e32 v159, v159, v154
	v_and_b32_e32 v154, 0xffff0000, v156
	v_add_f32_e32 v160, v160, v154
	v_lshlrev_b32_e32 v154, 16, v157
	v_add_f32_e32 v161, v161, v154
	v_and_b32_e32 v154, 0xffff0000, v157
	v_add_f32_e32 v153, v153, v154
	v_add_f32_e32 v131, v131, v165
	s_waitcnt lgkmcnt(0)
	v_add_u32_e32 v154, 0x124e0, v144
	ds_read_b128 v[154:157], v154
	v_lshlrev_b32_e32 v165, 16, v168
	v_and_b32_e32 v168, 0xffff0000, v168
	v_add_f32_e32 v132, v132, v168
	v_lshlrev_b32_e32 v168, 16, v169
	v_add_f32_e32 v133, v133, v168
	v_and_b32_e32 v168, 0xffff0000, v169
	v_add_f32_e32 v158, v158, v168
	v_lshlrev_b32_e32 v168, 16, v170
	v_add_f32_e32 v159, v159, v168
	v_and_b32_e32 v168, 0xffff0000, v170
	v_add_f32_e32 v160, v160, v168
	v_lshlrev_b32_e32 v168, 16, v171
	v_add_f32_e32 v161, v161, v168
	v_and_b32_e32 v168, 0xffff0000, v171
	v_add_f32_e32 v153, v153, v168
	v_add_f32_e32 v131, v131, v165
	s_waitcnt lgkmcnt(0)
	v_lshlrev_b32_e32 v165, 16, v154
	v_add_f32_e32 v165, v131, v165
	v_and_b32_e32 v131, 0xffff0000, v154
	v_add_f32_e32 v154, v132, v131
	v_lshlrev_b32_e32 v131, 16, v155
	v_add_f32_e32 v166, v133, v131
	v_and_b32_e32 v131, 0xffff0000, v155
	v_add_f32_e32 v155, v158, v131
	v_lshlrev_b32_e32 v131, 16, v156
	v_add_f32_e32 v158, v159, v131
	v_and_b32_e32 v131, 0xffff0000, v156
	v_add_f32_e32 v156, v160, v131
	v_lshlrev_b32_e32 v131, 16, v157
	v_add_f32_e32 v159, v161, v131
	v_and_b32_e32 v131, 0xffff0000, v157
	v_add_f32_e32 v153, v153, v131
	ds_read_b128 v[130:133], v130
	s_waitcnt lgkmcnt(0)
	v_lshlrev_b32_e32 v157, 16, v130
	v_and_b32_e32 v130, 0xffff0000, v130
	v_add_f32_e32 v130, v154, v130
	v_lshlrev_b32_e32 v154, 16, v131
	v_and_b32_e32 v131, 0xffff0000, v131
	v_add_f32_e32 v157, v165, v157
	v_add_f32_e32 v131, v155, v131
	v_lshlrev_b32_e32 v155, 16, v132
	v_and_b32_e32 v132, 0xffff0000, v132
	v_add_f32_e32 v154, v166, v154
	v_add_f32_e32 v132, v156, v132
	v_lshlrev_b32_e32 v156, 16, v133
	v_and_b32_e32 v133, 0xffff0000, v133
	v_fma_f32 v145, v135, v157, -v145
	v_fma_f32 v130, v135, v130, -v146
	v_add_f32_e32 v155, v158, v155
	v_add_f32_e32 v133, v153, v133
	v_cvt_pk_bf16_f32 v130, v145, v130
	v_fma_f32 v145, v135, v154, -v147
	v_fma_f32 v131, v135, v131, -v148
	v_add_f32_e32 v156, v159, v156
	v_cvt_pk_bf16_f32 v131, v145, v131
	v_fma_f32 v145, v135, v155, -v149
	v_fma_f32 v132, v135, v132, -v150
	v_fma_f32 v133, v135, v133, -v152
	v_cvt_pk_bf16_f32 v132, v145, v132
	v_fma_f32 v145, v135, v156, -v151
	v_cvt_pk_bf16_f32 v133, v145, v133
	s_waitcnt vmcnt(15)
; __device__ __forceinline__ float bflo(unsigned u) { return __uint_as_float(u << 16); }
; __device__ __forceinline__ float bfhi(unsigned u) { return __uint_as_float(u & 0xffff0000u); }
; template <int W>
; __device__ __forceinline__ void pool_compute(const Params& p, int layer, int g, int dh, int tt, const int tidx) {
;     ...
;     for (int k4 = 0; k4 < 4; ++k4) {
;       const int ks = kb * 4 + k4;
;       float sum[8];
; #pragma unroll
;       for (int j = 0; j < 8; ++j) sum[j] = 0.f;
;       u32x4 x0 = *reinterpret_cast<const u32x4*>(xl + ks * 32);
; #pragma unroll
;       for (int i = 0; i < W; ++i) {
;         u32x4 xv = *reinterpret_cast<const u32x4*>(xl + ks * 32 - i * PXS);
;         sum[0] += bflo(xv.x); sum[1] += bfhi(xv.x); sum[2] += bflo(xv.y); sum[3] += bfhi(xv.y);
;         sum[4] += bflo(xv.z); sum[5] += bfhi(xv.z); sum[6] += bflo(xv.w); sum[7] += bfhi(xv.w);
;       }
;       u32x4 bfr;
;       bfr.x = pack2(sum[0] * inv - bflo(x0.x), sum[1] * inv - bfhi(x0.x));
;       bfr.y = pack2(sum[2] * inv - bflo(x0.y), sum[3] * inv - bfhi(x0.y));
;       bfr.z = pack2(sum[4] * inv - bflo(x0.z), sum[5] * inv - bfhi(x0.z));
;       bfr.w = pack2(sum[6] * inv - bflo(x0.w), sum[7] * inv - bfhi(x0.w));
; #pragma unroll
;       for (int d = 0; d < 4; ++d) acc[d] = __builtin_amdgcn_mfma_f32_32x32x16_bf16(as_bf16x8(av[k4][d]), as_bf16x8(bfr), acc[d], 0, 0, 0);
	v_mfma_f32_32x32x16_bf16 v[48:63], v[114:117], v[130:133], v[48:63]
	v_add_u32_e32 v114, 0x141e0, v144
	s_waitcnt vmcnt(13)
	v_mfma_f32_32x32x16_bf16 v[32:47], v[118:121], v[130:133], v[32:47]
	ds_read_b128 v[118:121], v114
	s_waitcnt vmcnt(11)
	v_mfma_f32_32x32x16_bf16 v[16:31], v[122:125], v[130:133], v[16:31]
	v_add_u32_e32 v122, 0x13fd0, v144
	ds_read_b128 v[122:125], v122
	s_waitcnt lgkmcnt(1)
	v_and_b32_e32 v115, 0xffff0000, v118
	v_lshlrev_b32_e32 v116, 16, v119
	v_and_b32_e32 v117, 0xffff0000, v119
	v_lshlrev_b32_e32 v114, 16, v118
	s_waitcnt lgkmcnt(0)
	v_lshlrev_b32_e32 v145, 16, v122
	s_waitcnt vmcnt(9)
	v_mfma_f32_32x32x16_bf16 v[0:15], v[126:129], v[130:133], v[0:15]
	v_add_f32_e32 v127, 0, v115
	v_and_b32_e32 v122, 0xffff0000, v122
	v_add_f32_e32 v128, 0, v116
	v_add_f32_e32 v127, v127, v122
	v_lshlrev_b32_e32 v122, 16, v123
	v_add_f32_e32 v129, 0, v117
	v_lshlrev_b32_e32 v118, 16, v120
	v_add_f32_e32 v128, v128, v122
	v_and_b32_e32 v122, 0xffff0000, v123
	v_add_f32_e32 v130, 0, v118
	v_and_b32_e32 v119, 0xffff0000, v120
	v_add_f32_e32 v129, v129, v122
	v_lshlrev_b32_e32 v122, 16, v124
	v_add_f32_e32 v131, 0, v119
	v_lshlrev_b32_e32 v120, 16, v121
	v_add_f32_e32 v130, v130, v122
	v_and_b32_e32 v122, 0xffff0000, v124
	v_add_f32_e32 v132, 0, v120
	v_and_b32_e32 v121, 0xffff0000, v121
	v_add_f32_e32 v131, v131, v122
	v_lshlrev_b32_e32 v122, 16, v125
	v_add_f32_e32 v133, 0, v121
	v_add_f32_e32 v132, v132, v122
	v_and_b32_e32 v122, 0xffff0000, v125
	v_add_f32_e32 v133, v133, v122
	v_add_u32_e32 v168, 0x13dc0, v144
	ds_read_b128 v[168:171], v168
	v_add_f32_e32 v126, 0, v114
	v_add_f32_e32 v126, v126, v145
	s_waitcnt lgkmcnt(0)
	v_add_u32_e32 v122, 0x13bb0, v144
	ds_read_b128 v[122:125], v122
	v_lshlrev_b32_e32 v145, 16, v168
	v_and_b32_e32 v168, 0xffff0000, v168
	v_add_f32_e32 v127, v127, v168
	v_lshlrev_b32_e32 v168, 16, v169
	v_add_f32_e32 v128, v128, v168
	v_and_b32_e32 v168, 0xffff0000, v169
	v_add_f32_e32 v129, v129, v168
	v_lshlrev_b32_e32 v168, 16, v170
	v_add_f32_e32 v130, v130, v168
	v_and_b32_e32 v168, 0xffff0000, v170
	v_add_f32_e32 v131, v131, v168
	v_lshlrev_b32_e32 v168, 16, v171
	v_add_f32_e32 v132, v132, v168
	v_and_b32_e32 v168, 0xffff0000, v171
	v_add_f32_e32 v133, v133, v168
	v_add_f32_e32 v126, v126, v145
	s_waitcnt lgkmcnt(0)
	v_add_u32_e32 v168, 0x139a0, v144
	ds_read_b128 v[168:171], v168
	v_lshlrev_b32_e32 v145, 16, v122
	v_and_b32_e32 v122, 0xffff0000, v122
	v_add_f32_e32 v127, v127, v122
	v_lshlrev_b32_e32 v122, 16, v123
	v_add_f32_e32 v128, v128, v122
	v_and_b32_e32 v122, 0xffff0000, v123
	v_add_f32_e32 v129, v129, v122
	v_lshlrev_b32_e32 v122, 16, v124
	v_add_f32_e32 v130, v130, v122
	v_and_b32_e32 v122, 0xffff0000, v124
	v_add_f32_e32 v131, v131, v122
	v_lshlrev_b32_e32 v122, 16, v125
	v_add_f32_e32 v132, v132, v122
	v_and_b32_e32 v122, 0xffff0000, v125
	v_add_f32_e32 v133, v133, v122
	v_add_f32_e32 v126, v126, v145
	s_waitcnt lgkmcnt(0)
	v_add_u32_e32 v122, 0x13790, v144
	ds_read_b128 v[122:125], v122
	v_lshlrev_b32_e32 v145, 16, v168
	v_and_b32_e32 v168, 0xffff0000, v168
	v_add_f32_e32 v127, v127, v168
	v_lshlrev_b32_e32 v168, 16, v169
	v_add_f32_e32 v128, v128, v168
	v_and_b32_e32 v168, 0xffff0000, v169
	v_add_f32_e32 v129, v129, v168
	v_lshlrev_b32_e32 v168, 16, v170
	v_add_f32_e32 v130, v130, v168
	v_and_b32_e32 v168, 0xffff0000, v170
	v_add_f32_e32 v131, v131, v168
	v_lshlrev_b32_e32 v168, 16, v171
	v_add_f32_e32 v132, v132, v168
	v_and_b32_e32 v168, 0xffff0000, v171
	v_add_f32_e32 v133, v133, v168
	v_add_f32_e32 v126, v126, v145
	s_waitcnt lgkmcnt(0)
	v_add_u32_e32 v168, 0x13580, v144
	ds_read_b128 v[168:171], v168
	v_lshlrev_b32_e32 v145, 16, v122
	v_and_b32_e32 v122, 0xffff0000, v122
	v_add_f32_e32 v127, v127, v122
	v_lshlrev_b32_e32 v122, 16, v123
	v_add_f32_e32 v128, v128, v122
	v_and_b32_e32 v122, 0xffff0000, v123
	v_add_f32_e32 v129, v129, v122
	v_lshlrev_b32_e32 v122, 16, v124
	v_add_f32_e32 v130, v130, v122
	v_and_b32_e32 v122, 0xffff0000, v124
	v_add_f32_e32 v131, v131, v122
	v_lshlrev_b32_e32 v122, 16, v125
	v_add_f32_e32 v132, v132, v122
	v_and_b32_e32 v122, 0xffff0000, v125
	v_add_f32_e32 v133, v133, v122
	v_add_f32_e32 v126, v126, v145
	s_waitcnt lgkmcnt(0)
	v_add_u32_e32 v122, 0x13370, v144
	ds_read_b128 v[122:125], v122
	v_lshlrev_b32_e32 v145, 16, v168
	v_and_b32_e32 v168, 0xffff0000, v168
	v_add_f32_e32 v127, v127, v168
	v_lshlrev_b32_e32 v168, 16, v169
	v_add_f32_e32 v128, v128, v168
	v_and_b32_e32 v168, 0xffff0000, v169
	v_add_f32_e32 v129, v129, v168
	v_lshlrev_b32_e32 v168, 16, v170
	v_add_f32_e32 v130, v130, v168
	v_and_b32_e32 v168, 0xffff0000, v170
	v_add_f32_e32 v131, v131, v168
	v_lshlrev_b32_e32 v168, 16, v171
	v_add_f32_e32 v132, v132, v168
	v_and_b32_e32 v168, 0xffff0000, v171
	v_add_f32_e32 v133, v133, v168
	v_add_f32_e32 v126, v126, v145
	s_waitcnt lgkmcnt(0)
	v_add_u32_e32 v168, 0x13160, v144
	ds_read_b128 v[168:171], v168
	v_lshlrev_b32_e32 v145, 16, v122
	v_and_b32_e32 v122, 0xffff0000, v122
	v_add_f32_e32 v127, v127, v122
	v_lshlrev_b32_e32 v122, 16, v123
	v_add_f32_e32 v128, v128, v122
	v_and_b32_e32 v122, 0xffff0000, v123
	v_add_f32_e32 v129, v129, v122
	v_lshlrev_b32_e32 v122, 16, v124
	v_add_f32_e32 v130, v130, v122
	v_and_b32_e32 v122, 0xffff0000, v124
	v_add_f32_e32 v131, v131, v122
	v_lshlrev_b32_e32 v122, 16, v125
	v_add_f32_e32 v132, v132, v122
	v_and_b32_e32 v122, 0xffff0000, v125
	v_add_f32_e32 v133, v133, v122
	v_add_f32_e32 v126, v126, v145
	s_waitcnt lgkmcnt(0)
; __device__ __forceinline__ float bflo(unsigned u) { return __uint_as_float(u << 16); }
; __device__ __forceinline__ float bfhi(unsigned u) { return __uint_as_float(u & 0xffff0000u); }
; template <int W>
; __device__ __forceinline__ void pool_compute(const Params& p, int layer, int g, int dh, int tt, const int tidx) {
;     ...
;     for (int k4 = 0; k4 < 4; ++k4) {
;       const int ks = kb * 4 + k4;
;       float sum[8];
; #pragma unroll
;       for (int j = 0; j < 8; ++j) sum[j] = 0.f;
;       u32x4 x0 = *reinterpret_cast<const u32x4*>(xl + ks * 32);
; #pragma unroll
;       for (int i = 0; i < W; ++i) {
;         u32x4 xv = *reinterpret_cast<const u32x4*>(xl + ks * 32 - i * PXS);
;         sum[0] += bflo(xv.x); sum[1] += bfhi(xv.x); sum[2] += bflo(xv.y); sum[3] += bfhi(xv.y);
;         sum[4] += bflo(xv.z); sum[5] += bfhi(xv.z); sum[6] += bflo(xv.w); sum[7] += bfhi(xv.w);
;       }
;       u32x4 bfr;
;       bfr.x = pack2(sum[0] * inv - bflo(x0.x), sum[1] * inv - bfhi(x0.x));
;       bfr.y = pack2(sum[2] * inv - bflo(x0.y), sum[3] * inv - bfhi(x0.y));
;       bfr.z = pack2(sum[4] * inv - bflo(x0.z), sum[5] * inv - bfhi(x0.z));
;       bfr.w = pack2(sum[6] * inv - bflo(x0.w), sum[7] * inv - bfhi(x0.w));
; #pragma unroll
;       for (int d = 0; d < 4; ++d) acc[d] = __builtin_amdgcn_mfma_f32_32x32x16_bf16(as_bf16x8(av[k4][d]), as_bf16x8(bfr), acc[d], 0, 0, 0);
	v_add_u32_e32 v122, 0x12f50, v144
	ds_read_b128 v[122:125], v122
	v_lshlrev_b32_e32 v145, 16, v168
	v_and_b32_e32 v168, 0xffff0000, v168
	v_add_f32_e32 v127, v127, v168
	v_lshlrev_b32_e32 v168, 16, v169
	v_add_f32_e32 v128, v128, v168
	v_and_b32_e32 v168, 0xffff0000, v169
	v_add_f32_e32 v129, v129, v168
	v_lshlrev_b32_e32 v168, 16, v170
	v_add_f32_e32 v130, v130, v168
	v_and_b32_e32 v168, 0xffff0000, v170
	v_add_f32_e32 v131, v131, v168
	v_lshlrev_b32_e32 v168, 16, v171
	v_add_f32_e32 v132, v132, v168
	v_and_b32_e32 v168, 0xffff0000, v171
	v_add_f32_e32 v133, v133, v168
	v_add_f32_e32 v126, v126, v145
	s_waitcnt lgkmcnt(0)
	v_add_u32_e32 v168, 0x12d40, v144
	ds_read_b128 v[168:171], v168
	v_lshlrev_b32_e32 v145, 16, v122
	v_and_b32_e32 v122, 0xffff0000, v122
	v_add_f32_e32 v127, v127, v122
	v_lshlrev_b32_e32 v122, 16, v123
	v_add_f32_e32 v128, v128, v122
	v_and_b32_e32 v122, 0xffff0000, v123
	v_add_f32_e32 v129, v129, v122
	v_lshlrev_b32_e32 v122, 16, v124
	v_add_f32_e32 v130, v130, v122
	v_and_b32_e32 v122, 0xffff0000, v124
	v_add_f32_e32 v131, v131, v122
	v_lshlrev_b32_e32 v122, 16, v125
	v_add_f32_e32 v132, v132, v122
	v_and_b32_e32 v122, 0xffff0000, v125
	v_add_f32_e32 v133, v133, v122
	v_add_f32_e32 v126, v126, v145
	s_waitcnt lgkmcnt(0)
	v_add_u32_e32 v122, 0x12b30, v144
	ds_read_b128 v[122:125], v122
	v_lshlrev_b32_e32 v145, 16, v168
	v_and_b32_e32 v168, 0xffff0000, v168
	v_add_f32_e32 v127, v127, v168
	v_lshlrev_b32_e32 v168, 16, v169
	v_add_f32_e32 v128, v128, v168
	v_and_b32_e32 v168, 0xffff0000, v169
	v_add_f32_e32 v129, v129, v168
	v_lshlrev_b32_e32 v168, 16, v170
	v_add_f32_e32 v130, v130, v168
	v_and_b32_e32 v168, 0xffff0000, v170
	v_add_f32_e32 v131, v131, v168
	v_lshlrev_b32_e32 v168, 16, v171
	v_add_f32_e32 v132, v132, v168
	v_and_b32_e32 v168, 0xffff0000, v171
	v_add_f32_e32 v133, v133, v168
	v_add_f32_e32 v126, v126, v145
	s_waitcnt lgkmcnt(0)
	v_add_u32_e32 v168, 0x12920, v144
	ds_read_b128 v[168:171], v168
	v_lshlrev_b32_e32 v145, 16, v122
	v_and_b32_e32 v122, 0xffff0000, v122
	v_add_f32_e32 v127, v127, v122
	v_lshlrev_b32_e32 v122, 16, v123
	v_add_f32_e32 v128, v128, v122
	v_and_b32_e32 v122, 0xffff0000, v123
	v_add_f32_e32 v129, v129, v122
	v_lshlrev_b32_e32 v122, 16, v124
	v_add_f32_e32 v130, v130, v122
	v_and_b32_e32 v122, 0xffff0000, v124
	v_add_f32_e32 v131, v131, v122
	v_lshlrev_b32_e32 v122, 16, v125
	v_add_f32_e32 v132, v132, v122
	v_and_b32_e32 v122, 0xffff0000, v125
	v_add_f32_e32 v133, v133, v122
	v_add_f32_e32 v126, v126, v145
	s_waitcnt lgkmcnt(0)
	v_add_u32_e32 v122, 0x12710, v144
	ds_read_b128 v[122:125], v122
	v_lshlrev_b32_e32 v145, 16, v168
	v_and_b32_e32 v168, 0xffff0000, v168
	v_add_f32_e32 v127, v127, v168
	v_lshlrev_b32_e32 v168, 16, v169
	v_add_f32_e32 v128, v128, v168
	v_and_b32_e32 v168, 0xffff0000, v169
	v_add_f32_e32 v129, v129, v168
	v_lshlrev_b32_e32 v168, 16, v170
	v_add_f32_e32 v130, v130, v168
	v_and_b32_e32 v168, 0xffff0000, v170
	v_add_f32_e32 v131, v131, v168
	v_lshlrev_b32_e32 v168, 16, v171
	v_add_f32_e32 v132, v132, v168
	v_and_b32_e32 v168, 0xffff0000, v171
	v_add_f32_e32 v133, v133, v168
	v_add_f32_e32 v126, v126, v145
	s_waitcnt lgkmcnt(0)
	v_add_u32_e32 v168, 0x12500, v144
	ds_read_b128 v[168:171], v168
	v_lshlrev_b32_e32 v145, 16, v122
	v_and_b32_e32 v122, 0xffff0000, v122
	v_add_f32_e32 v127, v127, v122
	v_lshlrev_b32_e32 v122, 16, v123
	v_add_f32_e32 v128, v128, v122
	v_and_b32_e32 v122, 0xffff0000, v123
	v_add_f32_e32 v129, v129, v122
	v_lshlrev_b32_e32 v122, 16, v124
	v_add_f32_e32 v130, v130, v122
	v_and_b32_e32 v122, 0xffff0000, v124
	v_add_f32_e32 v131, v131, v122
	v_lshlrev_b32_e32 v122, 16, v125
	v_add_f32_e32 v132, v132, v122
	v_and_b32_e32 v122, 0xffff0000, v125
	v_add_f32_e32 v133, v133, v122
	v_add_f32_e32 v126, v126, v145
	s_waitcnt lgkmcnt(0)
	v_add_u32_e32 v122, 0x122f0, v144
	ds_read_b128 v[122:125], v122
	v_lshlrev_b32_e32 v145, 16, v168
	v_and_b32_e32 v168, 0xffff0000, v168
	v_add_f32_e32 v127, v127, v168
	v_lshlrev_b32_e32 v168, 16, v169
	v_add_f32_e32 v128, v128, v168
	v_and_b32_e32 v168, 0xffff0000, v169
	v_add_f32_e32 v129, v129, v168
	v_lshlrev_b32_e32 v168, 16, v170
	v_add_f32_e32 v130, v130, v168
	v_and_b32_e32 v168, 0xffff0000, v170
	v_add_f32_e32 v131, v131, v168
	v_lshlrev_b32_e32 v168, 16, v171
	v_add_f32_e32 v132, v132, v168
	v_and_b32_e32 v168, 0xffff0000, v171
	v_add_f32_e32 v133, v133, v168
	v_add_f32_e32 v126, v126, v145
	s_waitcnt lgkmcnt(0)
	v_lshlrev_b32_e32 v145, 16, v122
	v_and_b32_e32 v122, 0xffff0000, v122
	v_add_f32_e32 v126, v126, v145
	v_add_f32_e32 v122, v127, v122
	v_lshlrev_b32_e32 v127, 16, v123
	v_and_b32_e32 v123, 0xffff0000, v123
	v_add_f32_e32 v127, v128, v127
	v_add_f32_e32 v123, v129, v123
	v_lshlrev_b32_e32 v128, 16, v124
	v_and_b32_e32 v124, 0xffff0000, v124
	v_fma_f32 v114, v135, v126, -v114
	v_fma_f32 v115, v135, v122, -v115
	v_add_f32_e32 v128, v130, v128
	v_add_f32_e32 v124, v131, v124
	v_lshlrev_b32_e32 v129, 16, v125
	v_cvt_pk_bf16_f32 v114, v114, v115
	v_fma_f32 v115, v135, v127, -v116
	v_fma_f32 v116, v135, v123, -v117
	v_add_f32_e32 v129, v132, v129
	v_and_b32_e32 v125, 0xffff0000, v125
	v_cvt_pk_bf16_f32 v115, v115, v116
	v_fma_f32 v116, v135, v128, -v118
	v_fma_f32 v117, v135, v124, -v119
	v_add_f32_e32 v125, v133, v125
	v_cvt_pk_bf16_f32 v116, v116, v117
	v_fma_f32 v117, v135, v129, -v120
	v_fma_f32 v118, v135, v125, -v121
	v_cvt_pk_bf16_f32 v117, v117, v118
	s_nop 0
	v_mfma_f32_32x32x16_bf16 v[48:63], v[98:101], v[114:117], v[48:63]
	v_add_u32_e32 v98, 0x14200, v144
	v_mfma_f32_32x32x16_bf16 v[32:47], v[102:105], v[114:117], v[32:47]
	ds_read_b128 v[102:105], v98
	v_mfma_f32_32x32x16_bf16 v[16:31], v[106:109], v[114:117], v[16:31]
	v_add_u32_e32 v106, 0x13ff0, v144
	ds_read_b128 v[106:109], v106
	s_waitcnt lgkmcnt(1)
; __device__ __forceinline__ float bflo(unsigned u) { return __uint_as_float(u << 16); }
; __device__ __forceinline__ float bfhi(unsigned u) { return __uint_as_float(u & 0xffff0000u); }
; template <int W>
; __device__ __forceinline__ void pool_compute(const Params& p, int layer, int g, int dh, int tt, const int tidx) {
;     ...
;     for (int k4 = 0; k4 < 4; ++k4) {
;       const int ks = kb * 4 + k4;
;       float sum[8];
; #pragma unroll
;       for (int j = 0; j < 8; ++j) sum[j] = 0.f;
;       u32x4 x0 = *reinterpret_cast<const u32x4*>(xl + ks * 32);
; #pragma unroll
;       for (int i = 0; i < W; ++i) {
;         u32x4 xv = *reinterpret_cast<const u32x4*>(xl + ks * 32 - i * PXS);
;         sum[0] += bflo(xv.x); sum[1] += bfhi(xv.x); sum[2] += bflo(xv.y); sum[3] += bfhi(xv.y);
;         sum[4] += bflo(xv.z); sum[5] += bfhi(xv.z); sum[6] += bflo(xv.w); sum[7] += bfhi(xv.w);
;       }
;       u32x4 bfr;
;       bfr.x = pack2(sum[0] * inv - bflo(x0.x), sum[1] * inv - bfhi(x0.x));
;       bfr.y = pack2(sum[2] * inv - bflo(x0.y), sum[3] * inv - bfhi(x0.y));
;       bfr.z = pack2(sum[4] * inv - bflo(x0.z), sum[5] * inv - bfhi(x0.z));
;       bfr.w = pack2(sum[6] * inv - bflo(x0.w), sum[7] * inv - bfhi(x0.w));
; #pragma unroll
;       for (int d = 0; d < 4; ++d) acc[d] = __builtin_amdgcn_mfma_f32_32x32x16_bf16(as_bf16x8(av[k4][d]), as_bf16x8(bfr), acc[d], 0, 0, 0);
	v_and_b32_e32 v99, 0xffff0000, v102
	v_lshlrev_b32_e32 v100, 16, v103
	v_and_b32_e32 v101, 0xffff0000, v103
	v_lshlrev_b32_e32 v98, 16, v102
	s_waitcnt lgkmcnt(0)
	v_lshlrev_b32_e32 v118, 16, v106
	s_waitcnt vmcnt(8)
	v_mfma_f32_32x32x16_bf16 v[0:15], v[110:113], v[114:117], v[0:15]
	v_add_f32_e32 v111, 0, v99
	v_and_b32_e32 v106, 0xffff0000, v106
	v_add_f32_e32 v112, 0, v100
	v_add_f32_e32 v111, v111, v106
	v_lshlrev_b32_e32 v106, 16, v107
	v_add_f32_e32 v113, 0, v101
	v_lshlrev_b32_e32 v102, 16, v104
	v_add_f32_e32 v112, v112, v106
	v_and_b32_e32 v106, 0xffff0000, v107
	v_add_f32_e32 v114, 0, v102
	v_and_b32_e32 v103, 0xffff0000, v104
	v_add_f32_e32 v113, v113, v106
	v_lshlrev_b32_e32 v106, 16, v108
	v_add_f32_e32 v115, 0, v103
	v_lshlrev_b32_e32 v104, 16, v105
	v_add_f32_e32 v114, v114, v106
	v_and_b32_e32 v106, 0xffff0000, v108
	v_add_f32_e32 v116, 0, v104
	v_and_b32_e32 v105, 0xffff0000, v105
	v_add_f32_e32 v115, v115, v106
	v_lshlrev_b32_e32 v106, 16, v109
	v_add_f32_e32 v117, 0, v105
	v_add_f32_e32 v116, v116, v106
	v_and_b32_e32 v106, 0xffff0000, v109
	v_add_f32_e32 v117, v117, v106
	v_add_u32_e32 v106, 0x13de0, v144
	ds_read_b128 v[106:109], v106
	v_add_f32_e32 v110, 0, v98
	v_add_f32_e32 v110, v110, v118
	s_waitcnt lgkmcnt(0)
	v_add_u32_e32 v168, 0x13bd0, v144
	ds_read_b128 v[168:171], v168
	v_lshlrev_b32_e32 v118, 16, v106
	v_and_b32_e32 v106, 0xffff0000, v106
	v_add_f32_e32 v111, v111, v106
	v_lshlrev_b32_e32 v106, 16, v107
	v_add_f32_e32 v112, v112, v106
	v_and_b32_e32 v106, 0xffff0000, v107
	v_add_f32_e32 v113, v113, v106
	v_lshlrev_b32_e32 v106, 16, v108
	v_add_f32_e32 v114, v114, v106
	v_and_b32_e32 v106, 0xffff0000, v108
	v_add_f32_e32 v115, v115, v106
	v_lshlrev_b32_e32 v106, 16, v109
	v_add_f32_e32 v116, v116, v106
	v_and_b32_e32 v106, 0xffff0000, v109
	v_add_f32_e32 v117, v117, v106
	v_add_f32_e32 v110, v110, v118
	s_waitcnt lgkmcnt(0)
	v_add_u32_e32 v106, 0x139c0, v144
	ds_read_b128 v[106:109], v106
	v_lshlrev_b32_e32 v118, 16, v168
	v_and_b32_e32 v168, 0xffff0000, v168
	v_add_f32_e32 v111, v111, v168
	v_lshlrev_b32_e32 v168, 16, v169
	v_add_f32_e32 v112, v112, v168
	v_and_b32_e32 v168, 0xffff0000, v169
	v_add_f32_e32 v113, v113, v168
	v_lshlrev_b32_e32 v168, 16, v170
	v_add_f32_e32 v114, v114, v168
	v_and_b32_e32 v168, 0xffff0000, v170
	v_add_f32_e32 v115, v115, v168
	v_lshlrev_b32_e32 v168, 16, v171
	v_add_f32_e32 v116, v116, v168
	v_and_b32_e32 v168, 0xffff0000, v171
	v_add_f32_e32 v117, v117, v168
	v_add_f32_e32 v110, v110, v118
	s_waitcnt lgkmcnt(0)
	v_add_u32_e32 v168, 0x137b0, v144
	ds_read_b128 v[168:171], v168
	v_lshlrev_b32_e32 v118, 16, v106
	v_and_b32_e32 v106, 0xffff0000, v106
	v_add_f32_e32 v111, v111, v106
	v_lshlrev_b32_e32 v106, 16, v107
	v_add_f32_e32 v112, v112, v106
	v_and_b32_e32 v106, 0xffff0000, v107
	v_add_f32_e32 v113, v113, v106
	v_lshlrev_b32_e32 v106, 16, v108
	v_add_f32_e32 v114, v114, v106
	v_and_b32_e32 v106, 0xffff0000, v108
	v_add_f32_e32 v115, v115, v106
	v_lshlrev_b32_e32 v106, 16, v109
	v_add_f32_e32 v116, v116, v106
	v_and_b32_e32 v106, 0xffff0000, v109
	v_add_f32_e32 v117, v117, v106
	v_add_f32_e32 v110, v110, v118
	s_waitcnt lgkmcnt(0)
	v_add_u32_e32 v106, 0x135a0, v144
	ds_read_b128 v[106:109], v106
	v_lshlrev_b32_e32 v118, 16, v168
	v_and_b32_e32 v168, 0xffff0000, v168
	v_add_f32_e32 v111, v111, v168
	v_lshlrev_b32_e32 v168, 16, v169
	v_add_f32_e32 v112, v112, v168
	v_and_b32_e32 v168, 0xffff0000, v169
	v_add_f32_e32 v113, v113, v168
	v_lshlrev_b32_e32 v168, 16, v170
	v_add_f32_e32 v114, v114, v168
	v_and_b32_e32 v168, 0xffff0000, v170
	v_add_f32_e32 v115, v115, v168
	v_lshlrev_b32_e32 v168, 16, v171
	v_add_f32_e32 v116, v116, v168
	v_and_b32_e32 v168, 0xffff0000, v171
	v_add_f32_e32 v117, v117, v168
	v_add_f32_e32 v110, v110, v118
	s_waitcnt lgkmcnt(0)
	v_lshlrev_b32_e32 v118, 16, v106
	v_and_b32_e32 v106, 0xffff0000, v106
	v_add_f32_e32 v119, v111, v106
	v_lshlrev_b32_e32 v106, 16, v107
	v_add_f32_e32 v120, v112, v106
	v_and_b32_e32 v106, 0xffff0000, v107
	v_add_f32_e32 v121, v113, v106
	v_lshlrev_b32_e32 v106, 16, v108
	v_add_f32_e32 v114, v114, v106
	v_and_b32_e32 v106, 0xffff0000, v108
	v_add_f32_e32 v115, v115, v106
	v_lshlrev_b32_e32 v106, 16, v109
	v_add_f32_e32 v116, v116, v106
	v_and_b32_e32 v106, 0xffff0000, v109
	v_add_f32_e32 v117, v117, v106
	v_add_u32_e32 v106, 0x13390, v144
	v_add_f32_e32 v118, v110, v118
	ds_read_b128 v[110:113], v106
	s_waitcnt lgkmcnt(0)
	v_lshlrev_b32_e32 v106, 16, v110
	v_and_b32_e32 v107, 0xffff0000, v110
	v_lshlrev_b32_e32 v110, 16, v112
	v_lshlrev_b32_e32 v108, 16, v111
	v_and_b32_e32 v109, 0xffff0000, v111
	v_add_f32_e32 v110, v114, v110
	v_and_b32_e32 v111, 0xffff0000, v112
	v_lshlrev_b32_e32 v112, 16, v113
	v_and_b32_e32 v113, 0xffff0000, v113
	v_add_u32_e32 v114, 0x13180, v144
	v_add_f32_e32 v111, v115, v111
	v_add_f32_e32 v112, v116, v112
	v_add_f32_e32 v113, v117, v113
	ds_read_b128 v[114:117], v114
	v_add_f32_e32 v106, v118, v106
	v_add_f32_e32 v107, v119, v107
	v_add_f32_e32 v108, v120, v108
	v_add_f32_e32 v109, v121, v109
	s_waitcnt lgkmcnt(0)
	v_lshlrev_b32_e32 v118, 16, v114
	v_add_f32_e32 v118, v106, v118
	v_and_b32_e32 v106, 0xffff0000, v114
	v_add_f32_e32 v114, v107, v106
	v_lshlrev_b32_e32 v106, 16, v115
	v_add_f32_e32 v119, v108, v106
	v_and_b32_e32 v106, 0xffff0000, v115
	v_add_f32_e32 v115, v109, v106
	v_lshlrev_b32_e32 v106, 16, v116
	v_add_f32_e32 v110, v110, v106
	v_and_b32_e32 v106, 0xffff0000, v116
	v_add_f32_e32 v111, v111, v106
	v_lshlrev_b32_e32 v106, 16, v117
	v_add_f32_e32 v112, v112, v106
	v_and_b32_e32 v106, 0xffff0000, v117
	v_add_f32_e32 v113, v113, v106
	v_add_u32_e32 v106, 0x12f70, v144
	ds_read_b128 v[106:109], v106
	s_waitcnt lgkmcnt(0)
; __device__ __forceinline__ float bflo(unsigned u) { return __uint_as_float(u << 16); }
; __device__ __forceinline__ float bfhi(unsigned u) { return __uint_as_float(u & 0xffff0000u); }
; template <int W>
; __device__ __forceinline__ void pool_compute(const Params& p, int layer, int g, int dh, int tt, const int tidx) {
;     ...
;     for (int k4 = 0; k4 < 4; ++k4) {
;       const int ks = kb * 4 + k4;
;       float sum[8];
; #pragma unroll
;       for (int j = 0; j < 8; ++j) sum[j] = 0.f;
;       u32x4 x0 = *reinterpret_cast<const u32x4*>(xl + ks * 32);
; #pragma unroll
;       for (int i = 0; i < W; ++i) {
;         u32x4 xv = *reinterpret_cast<const u32x4*>(xl + ks * 32 - i * PXS);
;         sum[0] += bflo(xv.x); sum[1] += bfhi(xv.x); sum[2] += bflo(xv.y); sum[3] += bfhi(xv.y);
;         sum[4] += bflo(xv.z); sum[5] += bfhi(xv.z); sum[6] += bflo(xv.w); sum[7] += bfhi(xv.w);
;       }
;       u32x4 bfr;
;       bfr.x = pack2(sum[0] * inv - bflo(x0.x), sum[1] * inv - bfhi(x0.x));
;       bfr.y = pack2(sum[2] * inv - bflo(x0.y), sum[3] * inv - bfhi(x0.y));
;       bfr.z = pack2(sum[4] * inv - bflo(x0.z), sum[5] * inv - bfhi(x0.z));
;       bfr.w = pack2(sum[6] * inv - bflo(x0.w), sum[7] * inv - bfhi(x0.w));
; #pragma unroll
;       for (int d = 0; d < 4; ++d) acc[d] = __builtin_amdgcn_mfma_f32_32x32x16_bf16(as_bf16x8(av[k4][d]), as_bf16x8(bfr), acc[d], 0, 0, 0);
	v_add_u32_e32 v168, 0x12d60, v144
	ds_read_b128 v[168:171], v168
	v_lshlrev_b32_e32 v116, 16, v106
	v_and_b32_e32 v106, 0xffff0000, v106
	v_add_f32_e32 v114, v114, v106
	v_lshlrev_b32_e32 v106, 16, v107
	v_add_f32_e32 v117, v119, v106
	v_and_b32_e32 v106, 0xffff0000, v107
	v_add_f32_e32 v115, v115, v106
	v_lshlrev_b32_e32 v106, 16, v108
	v_add_f32_e32 v110, v110, v106
	v_and_b32_e32 v106, 0xffff0000, v108
	v_add_f32_e32 v111, v111, v106
	v_lshlrev_b32_e32 v106, 16, v109
	v_add_f32_e32 v112, v112, v106
	v_and_b32_e32 v106, 0xffff0000, v109
	v_add_f32_e32 v113, v113, v106
	v_add_f32_e32 v116, v118, v116
	s_waitcnt lgkmcnt(0)
	v_add_u32_e32 v106, 0x12b50, v144
	ds_read_b128 v[106:109], v106
	v_lshlrev_b32_e32 v118, 16, v168
	v_and_b32_e32 v168, 0xffff0000, v168
	v_add_f32_e32 v114, v114, v168
	v_lshlrev_b32_e32 v168, 16, v169
	v_add_f32_e32 v117, v117, v168
	v_and_b32_e32 v168, 0xffff0000, v169
	v_add_f32_e32 v115, v115, v168
	v_lshlrev_b32_e32 v168, 16, v170
	v_add_f32_e32 v110, v110, v168
	v_and_b32_e32 v168, 0xffff0000, v170
	v_add_f32_e32 v111, v111, v168
	v_lshlrev_b32_e32 v168, 16, v171
	v_add_f32_e32 v112, v112, v168
	v_and_b32_e32 v168, 0xffff0000, v171
	v_add_f32_e32 v113, v113, v168
	v_add_f32_e32 v116, v116, v118
	s_waitcnt lgkmcnt(0)
	v_add_u32_e32 v168, 0x12940, v144
	ds_read_b128 v[168:171], v168
	v_lshlrev_b32_e32 v118, 16, v106
	v_and_b32_e32 v106, 0xffff0000, v106
	v_add_f32_e32 v114, v114, v106
	v_lshlrev_b32_e32 v106, 16, v107
	v_add_f32_e32 v117, v117, v106
	v_and_b32_e32 v106, 0xffff0000, v107
	v_add_f32_e32 v115, v115, v106
	v_lshlrev_b32_e32 v106, 16, v108
	v_add_f32_e32 v110, v110, v106
	v_and_b32_e32 v106, 0xffff0000, v108
	v_add_f32_e32 v111, v111, v106
	v_lshlrev_b32_e32 v106, 16, v109
	v_add_f32_e32 v112, v112, v106
	v_and_b32_e32 v106, 0xffff0000, v109
	v_add_f32_e32 v113, v113, v106
	v_add_f32_e32 v116, v116, v118
	s_waitcnt lgkmcnt(0)
	v_add_u32_e32 v106, 0x12730, v144
	ds_read_b128 v[106:109], v106
	v_lshlrev_b32_e32 v118, 16, v168
	v_and_b32_e32 v168, 0xffff0000, v168
	v_add_f32_e32 v114, v114, v168
	v_lshlrev_b32_e32 v168, 16, v169
	v_add_f32_e32 v117, v117, v168
	v_and_b32_e32 v168, 0xffff0000, v169
	v_add_f32_e32 v115, v115, v168
	v_lshlrev_b32_e32 v168, 16, v170
	v_add_f32_e32 v110, v110, v168
	v_and_b32_e32 v168, 0xffff0000, v170
	v_add_f32_e32 v111, v111, v168
	v_lshlrev_b32_e32 v168, 16, v171
	v_add_f32_e32 v112, v112, v168
	v_and_b32_e32 v168, 0xffff0000, v171
	v_add_f32_e32 v113, v113, v168
	v_add_f32_e32 v116, v116, v118
	s_waitcnt lgkmcnt(0)
	v_add_u32_e32 v168, 0x12520, v144
	ds_read_b128 v[168:171], v168
	v_lshlrev_b32_e32 v118, 16, v106
	v_and_b32_e32 v106, 0xffff0000, v106
	v_add_f32_e32 v114, v114, v106
	v_lshlrev_b32_e32 v106, 16, v107
	v_add_f32_e32 v117, v117, v106
	v_and_b32_e32 v106, 0xffff0000, v107
	v_add_f32_e32 v115, v115, v106
	v_lshlrev_b32_e32 v106, 16, v108
	v_add_f32_e32 v110, v110, v106
	v_and_b32_e32 v106, 0xffff0000, v108
	v_add_f32_e32 v111, v111, v106
	v_lshlrev_b32_e32 v106, 16, v109
	v_add_f32_e32 v112, v112, v106
	v_and_b32_e32 v106, 0xffff0000, v109
	v_add_f32_e32 v113, v113, v106
	v_add_f32_e32 v116, v116, v118
	s_waitcnt lgkmcnt(0)
	v_add_u32_e32 v106, 0x12310, v144
	ds_read_b128 v[106:109], v106
	v_lshlrev_b32_e32 v118, 16, v168
	v_and_b32_e32 v168, 0xffff0000, v168
	v_add_f32_e32 v114, v114, v168
	v_lshlrev_b32_e32 v168, 16, v169
	v_add_f32_e32 v117, v117, v168
	v_and_b32_e32 v168, 0xffff0000, v169
	v_add_f32_e32 v115, v115, v168
	v_lshlrev_b32_e32 v168, 16, v170
	v_add_f32_e32 v110, v110, v168
	v_and_b32_e32 v168, 0xffff0000, v170
	v_add_f32_e32 v111, v111, v168
	v_lshlrev_b32_e32 v168, 16, v171
	v_add_f32_e32 v112, v112, v168
	v_and_b32_e32 v168, 0xffff0000, v171
	v_add_f32_e32 v113, v113, v168
	v_add_f32_e32 v116, v116, v118
	s_waitcnt lgkmcnt(0)
	v_lshlrev_b32_e32 v118, 16, v106
	v_and_b32_e32 v106, 0xffff0000, v106
	v_add_f32_e32 v116, v116, v118
	v_add_f32_e32 v106, v114, v106
	v_lshlrev_b32_e32 v114, 16, v107
	v_and_b32_e32 v107, 0xffff0000, v107
	v_add_f32_e32 v114, v117, v114
	v_add_f32_e32 v107, v115, v107
	v_lshlrev_b32_e32 v115, 16, v108
	v_and_b32_e32 v108, 0xffff0000, v108
	v_fma_f32 v98, v135, v116, -v98
	v_fma_f32 v99, v135, v106, -v99
	v_add_f32_e32 v110, v110, v115
	v_add_f32_e32 v108, v111, v108
	v_lshlrev_b32_e32 v111, 16, v109
	v_cvt_pk_bf16_f32 v98, v98, v99
	v_fma_f32 v99, v135, v114, -v100
	v_fma_f32 v100, v135, v107, -v101
	v_add_f32_e32 v111, v112, v111
	v_and_b32_e32 v109, 0xffff0000, v109
	v_cvt_pk_bf16_f32 v99, v99, v100
	v_fma_f32 v100, v135, v110, -v102
	v_fma_f32 v101, v135, v108, -v103
	v_add_f32_e32 v109, v113, v109
	v_cvt_pk_bf16_f32 v100, v100, v101
	v_fma_f32 v101, v135, v111, -v104
	v_fma_f32 v102, v135, v109, -v105
	v_cvt_pk_bf16_f32 v101, v101, v102
	s_waitcnt vmcnt(7)
	v_mfma_f32_32x32x16_bf16 v[48:63], v[80:83], v[98:101], v[48:63]
	v_add_u32_e32 v80, 0x14220, v144
	s_waitcnt vmcnt(3)
	v_mfma_f32_32x32x16_bf16 v[16:31], v[88:91], v[98:101], v[16:31]
	ds_read_b128 v[88:91], v80
	s_waitcnt lgkmcnt(0)
	v_lshlrev_b32_e32 v83, 16, v90
	v_and_b32_e32 v82, 0xffff0000, v90
	v_mfma_f32_32x32x16_bf16 v[32:47], v[84:87], v[98:101], v[32:47]
	v_lshlrev_b32_e32 v86, 16, v88
	v_and_b32_e32 v87, 0xffff0000, v88
	v_add_u32_e32 v88, 0x14010, v144
	v_lshlrev_b32_e32 v84, 16, v89
	v_and_b32_e32 v85, 0xffff0000, v89
	v_lshlrev_b32_e32 v80, 16, v91
	v_and_b32_e32 v81, 0xffff0000, v91
	ds_read_b128 v[88:91], v88
	s_waitcnt vmcnt(1)
	v_mfma_f32_32x32x16_bf16 v[0:15], v[92:95], v[98:101], v[0:15]
	v_add_f32_e32 v93, 0, v87
	v_add_f32_e32 v94, 0, v84
	v_add_f32_e32 v95, 0, v85
	s_waitcnt lgkmcnt(0)
; __device__ __forceinline__ float bflo(unsigned u) { return __uint_as_float(u << 16); }
; __device__ __forceinline__ float bfhi(unsigned u) { return __uint_as_float(u & 0xffff0000u); }
; template <int W>
; __device__ __forceinline__ void pool_compute(const Params& p, int layer, int g, int dh, int tt, const int tidx) {
;     ...
;     for (int k4 = 0; k4 < 4; ++k4) {
;       const int ks = kb * 4 + k4;
;       float sum[8];
; #pragma unroll
;       for (int j = 0; j < 8; ++j) sum[j] = 0.f;
;       u32x4 x0 = *reinterpret_cast<const u32x4*>(xl + ks * 32);
; #pragma unroll
;       for (int i = 0; i < W; ++i) {
;         u32x4 xv = *reinterpret_cast<const u32x4*>(xl + ks * 32 - i * PXS);
;         sum[0] += bflo(xv.x); sum[1] += bfhi(xv.x); sum[2] += bflo(xv.y); sum[3] += bfhi(xv.y);
;         sum[4] += bflo(xv.z); sum[5] += bfhi(xv.z); sum[6] += bflo(xv.w); sum[7] += bfhi(xv.w);
;       }
;       u32x4 bfr;
;       bfr.x = pack2(sum[0] * inv - bflo(x0.x), sum[1] * inv - bfhi(x0.x));
;       bfr.y = pack2(sum[2] * inv - bflo(x0.y), sum[3] * inv - bfhi(x0.y));
;       bfr.z = pack2(sum[4] * inv - bflo(x0.z), sum[5] * inv - bfhi(x0.z));
;       bfr.w = pack2(sum[6] * inv - bflo(x0.w), sum[7] * inv - bfhi(x0.w));
; #pragma unroll
;       for (int d = 0; d < 4; ++d) acc[d] = __builtin_amdgcn_mfma_f32_32x32x16_bf16(as_bf16x8(av[k4][d]), as_bf16x8(bfr), acc[d], 0, 0, 0);
	v_lshlrev_b32_e32 v102, 16, v88
	v_and_b32_e32 v88, 0xffff0000, v88
	v_add_f32_e32 v93, v93, v88
	v_lshlrev_b32_e32 v88, 16, v89
	v_add_f32_e32 v94, v94, v88
	v_and_b32_e32 v88, 0xffff0000, v89
	v_add_f32_e32 v98, 0, v83
	v_add_f32_e32 v95, v95, v88
	v_lshlrev_b32_e32 v88, 16, v90
	v_add_f32_e32 v99, 0, v82
	v_add_f32_e32 v98, v98, v88
	v_and_b32_e32 v88, 0xffff0000, v90
	v_add_f32_e32 v100, 0, v80
	v_add_f32_e32 v99, v99, v88
	v_lshlrev_b32_e32 v88, 16, v91
	v_add_f32_e32 v101, 0, v81
	v_add_f32_e32 v100, v100, v88
	v_and_b32_e32 v88, 0xffff0000, v91
	v_add_f32_e32 v101, v101, v88
	v_add_u32_e32 v88, 0x13e00, v144
	ds_read_b128 v[88:91], v88
	v_add_f32_e32 v92, 0, v86
	v_add_f32_e32 v92, v92, v102
	s_waitcnt lgkmcnt(0)
	v_add_u32_e32 v168, 0x13bf0, v144
	ds_read_b128 v[168:171], v168
	v_lshlrev_b32_e32 v102, 16, v88
	v_and_b32_e32 v88, 0xffff0000, v88
	v_add_f32_e32 v93, v93, v88
	v_lshlrev_b32_e32 v88, 16, v89
	v_add_f32_e32 v94, v94, v88
	v_and_b32_e32 v88, 0xffff0000, v89
	v_add_f32_e32 v95, v95, v88
	v_lshlrev_b32_e32 v88, 16, v90
	v_add_f32_e32 v98, v98, v88
	v_and_b32_e32 v88, 0xffff0000, v90
	v_add_f32_e32 v99, v99, v88
	v_lshlrev_b32_e32 v88, 16, v91
	v_add_f32_e32 v100, v100, v88
	v_and_b32_e32 v88, 0xffff0000, v91
	v_add_f32_e32 v101, v101, v88
	v_add_f32_e32 v92, v92, v102
	s_waitcnt lgkmcnt(0)
	v_add_u32_e32 v88, 0x139e0, v144
	ds_read_b128 v[88:91], v88
	v_lshlrev_b32_e32 v102, 16, v168
	v_and_b32_e32 v168, 0xffff0000, v168
	v_add_f32_e32 v93, v93, v168
	v_lshlrev_b32_e32 v168, 16, v169
	v_add_f32_e32 v94, v94, v168
	v_and_b32_e32 v168, 0xffff0000, v169
	v_add_f32_e32 v95, v95, v168
	v_lshlrev_b32_e32 v168, 16, v170
	v_add_f32_e32 v98, v98, v168
	v_and_b32_e32 v168, 0xffff0000, v170
	v_add_f32_e32 v99, v99, v168
	v_lshlrev_b32_e32 v168, 16, v171
	v_add_f32_e32 v100, v100, v168
	v_and_b32_e32 v168, 0xffff0000, v171
	v_add_f32_e32 v101, v101, v168
	v_add_f32_e32 v92, v92, v102
	s_waitcnt lgkmcnt(0)
	v_add_u32_e32 v168, 0x137d0, v144
	ds_read_b128 v[168:171], v168
	v_lshlrev_b32_e32 v102, 16, v88
	v_and_b32_e32 v88, 0xffff0000, v88
	v_add_f32_e32 v93, v93, v88
	v_lshlrev_b32_e32 v88, 16, v89
	v_add_f32_e32 v94, v94, v88
	v_and_b32_e32 v88, 0xffff0000, v89
	v_add_f32_e32 v95, v95, v88
	v_lshlrev_b32_e32 v88, 16, v90
	v_add_f32_e32 v98, v98, v88
	v_and_b32_e32 v88, 0xffff0000, v90
	v_add_f32_e32 v99, v99, v88
	v_lshlrev_b32_e32 v88, 16, v91
	v_add_f32_e32 v100, v100, v88
	v_and_b32_e32 v88, 0xffff0000, v91
	v_add_f32_e32 v101, v101, v88
	v_add_f32_e32 v92, v92, v102
	s_waitcnt lgkmcnt(0)
	v_add_u32_e32 v88, 0x135c0, v144
	ds_read_b128 v[88:91], v88
	v_lshlrev_b32_e32 v102, 16, v168
	v_and_b32_e32 v168, 0xffff0000, v168
	v_add_f32_e32 v93, v93, v168
	v_lshlrev_b32_e32 v168, 16, v169
	v_add_f32_e32 v94, v94, v168
	v_and_b32_e32 v168, 0xffff0000, v169
	v_add_f32_e32 v95, v95, v168
	v_lshlrev_b32_e32 v168, 16, v170
	v_add_f32_e32 v98, v98, v168
	v_and_b32_e32 v168, 0xffff0000, v170
	v_add_f32_e32 v99, v99, v168
	v_lshlrev_b32_e32 v168, 16, v171
	v_add_f32_e32 v100, v100, v168
	v_and_b32_e32 v168, 0xffff0000, v171
	v_add_f32_e32 v101, v101, v168
	v_add_f32_e32 v92, v92, v102
	s_waitcnt lgkmcnt(0)
	v_lshlrev_b32_e32 v102, 16, v88
	v_and_b32_e32 v88, 0xffff0000, v88
	v_add_f32_e32 v103, v93, v88
	v_lshlrev_b32_e32 v88, 16, v89
	v_add_f32_e32 v104, v94, v88
	v_and_b32_e32 v88, 0xffff0000, v89
	v_add_f32_e32 v105, v95, v88
	v_lshlrev_b32_e32 v88, 16, v90
	v_add_f32_e32 v98, v98, v88
	v_and_b32_e32 v88, 0xffff0000, v90
	v_add_f32_e32 v99, v99, v88
	v_lshlrev_b32_e32 v88, 16, v91
	v_add_f32_e32 v100, v100, v88
	v_and_b32_e32 v88, 0xffff0000, v91
	v_add_f32_e32 v101, v101, v88
	v_add_u32_e32 v88, 0x133b0, v144
	v_add_f32_e32 v102, v92, v102
	ds_read_b128 v[92:95], v88
	s_waitcnt lgkmcnt(0)
	v_lshlrev_b32_e32 v88, 16, v92
	v_and_b32_e32 v89, 0xffff0000, v92
	v_lshlrev_b32_e32 v92, 16, v94
	v_lshlrev_b32_e32 v90, 16, v93
	v_and_b32_e32 v91, 0xffff0000, v93
	v_add_f32_e32 v92, v98, v92
	v_and_b32_e32 v93, 0xffff0000, v94
	v_lshlrev_b32_e32 v94, 16, v95
	v_and_b32_e32 v95, 0xffff0000, v95
	v_add_u32_e32 v98, 0x131a0, v144
	v_add_f32_e32 v93, v99, v93
	v_add_f32_e32 v94, v100, v94
	v_add_f32_e32 v95, v101, v95
	ds_read_b128 v[98:101], v98
	v_add_f32_e32 v88, v102, v88
	v_add_f32_e32 v89, v103, v89
	v_add_f32_e32 v90, v104, v90
	v_add_f32_e32 v91, v105, v91
	s_waitcnt lgkmcnt(0)
	v_lshlrev_b32_e32 v102, 16, v98
	v_add_f32_e32 v102, v88, v102
	v_and_b32_e32 v88, 0xffff0000, v98
	v_add_f32_e32 v98, v89, v88
	v_lshlrev_b32_e32 v88, 16, v99
	v_add_f32_e32 v103, v90, v88
	v_and_b32_e32 v88, 0xffff0000, v99
	v_add_f32_e32 v99, v91, v88
	v_lshlrev_b32_e32 v88, 16, v100
	v_add_f32_e32 v92, v92, v88
	v_and_b32_e32 v88, 0xffff0000, v100
	v_add_f32_e32 v93, v93, v88
	v_lshlrev_b32_e32 v88, 16, v101
	v_add_f32_e32 v94, v94, v88
	v_and_b32_e32 v88, 0xffff0000, v101
	v_add_f32_e32 v95, v95, v88
	v_add_u32_e32 v88, 0x12f90, v144
	ds_read_b128 v[88:91], v88
	s_waitcnt lgkmcnt(0)
	v_lshlrev_b32_e32 v100, 16, v88
	v_and_b32_e32 v88, 0xffff0000, v88
	v_add_f32_e32 v98, v98, v88
	v_lshlrev_b32_e32 v88, 16, v89
	v_add_f32_e32 v101, v103, v88
	v_and_b32_e32 v88, 0xffff0000, v89
	v_add_f32_e32 v99, v99, v88
	v_lshlrev_b32_e32 v88, 16, v90
	v_add_f32_e32 v100, v102, v100
	v_add_f32_e32 v102, v92, v88
	v_and_b32_e32 v88, 0xffff0000, v90
	v_add_f32_e32 v103, v93, v88
	v_lshlrev_b32_e32 v88, 16, v91
	v_add_f32_e32 v104, v94, v88
	v_and_b32_e32 v88, 0xffff0000, v91
	v_add_f32_e32 v105, v95, v88
	v_add_u32_e32 v88, 0x12d80, v144
	ds_read_b128 v[92:95], v88
	s_waitcnt lgkmcnt(0)
; __device__ __forceinline__ float bflo(unsigned u) { return __uint_as_float(u << 16); }
; __device__ __forceinline__ float bfhi(unsigned u) { return __uint_as_float(u & 0xffff0000u); }
; template <int W>
; __device__ __forceinline__ void pool_compute(const Params& p, int layer, int g, int dh, int tt, const int tidx) {
;     ...
;   for (int kb = 0; kb < 4; ++kb) {
;     ...
;     for (int k4 = 0; k4 < 4; ++k4) {
;       const int ks = kb * 4 + k4;
;       float sum[8];
; #pragma unroll
;       for (int j = 0; j < 8; ++j) sum[j] = 0.f;
;       u32x4 x0 = *reinterpret_cast<const u32x4*>(xl + ks * 32);
; #pragma unroll
;       for (int i = 0; i < W; ++i) {
;         u32x4 xv = *reinterpret_cast<const u32x4*>(xl + ks * 32 - i * PXS);
;         sum[0] += bflo(xv.x); sum[1] += bfhi(xv.x); sum[2] += bflo(xv.y); sum[3] += bfhi(xv.y);
;         sum[4] += bflo(xv.z); sum[5] += bfhi(xv.z); sum[6] += bflo(xv.w); sum[7] += bfhi(xv.w);
;       }
;       u32x4 bfr;
;       bfr.x = pack2(sum[0] * inv - bflo(x0.x), sum[1] * inv - bfhi(x0.x));
;       bfr.y = pack2(sum[2] * inv - bflo(x0.y), sum[3] * inv - bfhi(x0.y));
;       bfr.z = pack2(sum[4] * inv - bflo(x0.z), sum[5] * inv - bfhi(x0.z));
;       bfr.w = pack2(sum[6] * inv - bflo(x0.w), sum[7] * inv - bfhi(x0.w));
; #pragma unroll
;       for (int d = 0; d < 4; ++d) acc[d] = __builtin_amdgcn_mfma_f32_32x32x16_bf16(as_bf16x8(av[k4][d]), as_bf16x8(bfr), acc[d], 0, 0, 0);
;     }
	v_and_b32_e32 v89, 0xffff0000, v92
	v_lshlrev_b32_e32 v88, 16, v92
	v_add_f32_e32 v89, v98, v89
	v_lshlrev_b32_e32 v90, 16, v93
	v_and_b32_e32 v91, 0xffff0000, v93
	v_add_u32_e32 v98, 0x12b70, v144
	v_add_f32_e32 v88, v100, v88
	v_add_f32_e32 v90, v101, v90
	v_add_f32_e32 v91, v99, v91
	ds_read_b128 v[98:101], v98
	v_lshlrev_b32_e32 v92, 16, v94
	v_add_f32_e32 v92, v102, v92
	v_and_b32_e32 v93, 0xffff0000, v94
	v_add_f32_e32 v93, v103, v93
	s_waitcnt lgkmcnt(0)
	v_lshlrev_b32_e32 v102, 16, v98
	v_add_f32_e32 v102, v88, v102
	v_and_b32_e32 v88, 0xffff0000, v98
	v_add_f32_e32 v98, v89, v88
	v_lshlrev_b32_e32 v88, 16, v99
	v_add_f32_e32 v103, v90, v88
	v_and_b32_e32 v88, 0xffff0000, v99
	v_add_f32_e32 v99, v91, v88
	v_lshlrev_b32_e32 v88, 16, v100
	v_lshlrev_b32_e32 v94, 16, v95
	v_add_f32_e32 v92, v92, v88
	v_and_b32_e32 v88, 0xffff0000, v100
	v_add_f32_e32 v94, v104, v94
	v_and_b32_e32 v95, 0xffff0000, v95
	v_add_f32_e32 v93, v93, v88
	v_lshlrev_b32_e32 v88, 16, v101
	v_add_f32_e32 v95, v105, v95
	v_add_f32_e32 v94, v94, v88
	v_and_b32_e32 v88, 0xffff0000, v101
	v_add_f32_e32 v95, v95, v88
	v_add_u32_e32 v88, 0x12960, v144
	ds_read_b128 v[88:91], v88
	s_waitcnt lgkmcnt(0)
	v_add_u32_e32 v168, 0x12750, v144
	ds_read_b128 v[168:171], v168
	v_lshlrev_b32_e32 v100, 16, v88
	v_and_b32_e32 v88, 0xffff0000, v88
	v_add_f32_e32 v98, v98, v88
	v_lshlrev_b32_e32 v88, 16, v89
	v_add_f32_e32 v101, v103, v88
	v_and_b32_e32 v88, 0xffff0000, v89
	v_add_f32_e32 v99, v99, v88
	v_lshlrev_b32_e32 v88, 16, v90
	v_add_f32_e32 v92, v92, v88
	v_and_b32_e32 v88, 0xffff0000, v90
	v_add_f32_e32 v93, v93, v88
	v_lshlrev_b32_e32 v88, 16, v91
	v_add_f32_e32 v94, v94, v88
	v_and_b32_e32 v88, 0xffff0000, v91
	v_add_f32_e32 v95, v95, v88
	v_add_f32_e32 v100, v102, v100
	s_waitcnt lgkmcnt(0)
	v_add_u32_e32 v88, 0x12540, v144
	ds_read_b128 v[88:91], v88
	v_lshlrev_b32_e32 v102, 16, v168
	v_and_b32_e32 v168, 0xffff0000, v168
	v_add_f32_e32 v98, v98, v168
	v_lshlrev_b32_e32 v168, 16, v169
	v_add_f32_e32 v101, v101, v168
	v_and_b32_e32 v168, 0xffff0000, v169
	v_add_f32_e32 v99, v99, v168
	v_lshlrev_b32_e32 v168, 16, v170
	v_add_f32_e32 v92, v92, v168
	v_and_b32_e32 v168, 0xffff0000, v170
	v_add_f32_e32 v93, v93, v168
	v_lshlrev_b32_e32 v168, 16, v171
	v_add_f32_e32 v94, v94, v168
	v_and_b32_e32 v168, 0xffff0000, v171
	v_add_f32_e32 v95, v95, v168
	v_add_f32_e32 v100, v100, v102
	s_waitcnt lgkmcnt(0)
	v_lshlrev_b32_e32 v102, 16, v88
	v_and_b32_e32 v88, 0xffff0000, v88
	v_add_f32_e32 v103, v98, v88
	v_lshlrev_b32_e32 v88, 16, v89
	v_add_f32_e32 v104, v101, v88
	v_and_b32_e32 v88, 0xffff0000, v89
	v_add_u32_e32 v89, 0x12330, v144
	v_add_f32_e32 v102, v100, v102
	v_add_f32_e32 v105, v99, v88
	ds_read_b128 v[98:101], v89
	v_lshlrev_b32_e32 v88, 16, v90
	v_add_f32_e32 v106, v92, v88
	v_and_b32_e32 v88, 0xffff0000, v90
	v_add_f32_e32 v107, v93, v88
	v_lshlrev_b32_e32 v88, 16, v91
	v_add_f32_e32 v108, v94, v88
	v_and_b32_e32 v88, 0xffff0000, v91
	s_waitcnt lgkmcnt(0)
	v_lshlrev_b32_e32 v89, 16, v98
	v_and_b32_e32 v90, 0xffff0000, v98
	v_add_f32_e32 v88, v95, v88
	v_add_f32_e32 v89, v102, v89
	v_add_f32_e32 v90, v103, v90
	v_lshlrev_b32_e32 v91, 16, v99
	v_and_b32_e32 v92, 0xffff0000, v99
	v_lshlrev_b32_e32 v93, 16, v100
	v_and_b32_e32 v94, 0xffff0000, v100
	v_lshlrev_b32_e32 v95, 16, v101
	v_and_b32_e32 v98, 0xffff0000, v101
	v_add_f32_e32 v91, v104, v91
	v_add_f32_e32 v92, v105, v92
	v_add_f32_e32 v93, v106, v93
	v_add_f32_e32 v94, v107, v94
	v_add_f32_e32 v95, v108, v95
	v_add_f32_e32 v98, v88, v98
	v_fma_f32 v86, v135, v89, -v86
	v_fma_f32 v87, v135, v90, -v87
	v_cvt_pk_bf16_f32 v86, v86, v87
	v_fma_f32 v84, v135, v91, -v84
	v_fma_f32 v85, v135, v92, -v85
	v_cvt_pk_bf16_f32 v87, v84, v85
	v_fma_f32 v83, v135, v93, -v83
	v_fma_f32 v82, v135, v94, -v82
	v_cvt_pk_bf16_f32 v88, v83, v82
	v_fma_f32 v80, v135, v95, -v80
	v_fma_f32 v81, v135, v98, -v81
	v_cvt_pk_bf16_f32 v89, v80, v81
	s_nop 0
	v_mfma_f32_32x32x16_bf16 v[48:63], v[64:67], v[86:89], v[48:63]
	v_mfma_f32_32x32x16_bf16 v[32:47], v[68:71], v[86:89], v[32:47]
	v_mfma_f32_32x32x16_bf16 v[16:31], v[72:75], v[86:89], v[16:31]
	s_waitcnt vmcnt(0)
	v_mfma_f32_32x32x16_bf16 v[0:15], v[76:79], v[86:89], v[0:15]
	s_cbranch_scc1 .LBB0_185
; #define SCHED __builtin_amdgcn_sched_barrier(0)
; template <int W>
; __device__ __forceinline__ void pool_compute(const Params& p, int layer, int g, int dh, int tt, const int tidx) {
;     ...
;   u16* yo = yraw + (size_t)t * DM + g * 256;
;   f32x4 scv[4][4];
; #pragma unroll
;   for (int d = 0; d < 4; ++d)
; #pragma unroll
;     for (int rg = 0; rg < 4; ++rg) scv[d][rg] = *reinterpret_cast<const f32x4*>(psc + (dh * 4 + d) * 32 + 8 * rg + 4 * half);
;   SCHED;
; #pragma unroll
;   for (int d = 0; d < 4; ++d)
; #pragma unroll
;     for (int rg = 0; rg < 4; ++rg) {
;       int dd = (dh * 4 + d) * 32 + 8 * rg + 4 * half;
;       f32x4 sc = scv[d][rg];
;       u32x2 o = {pack2(acc[d][rg * 4 + 0] * sc[0], acc[d][rg * 4 + 1] * sc[1]), pack2(acc[d][rg * 4 + 2] * sc[2], acc[d][rg * 4 + 3] * sc[3])};
;       *reinterpret_cast<u32x2*>(yo + dd) = o;
;     }
	v_mov_b32_e32 v135, v163
	v_lshl_add_u64 v[64:65], s[78:79], 0, v[134:135]
	v_lshlrev_b32_e32 v66, 9, v138
	v_mov_b32_e32 v67, v163
	v_lshl_add_u64 v[126:127], v[64:65], 0, v[66:67]
	global_load_dwordx4 v[64:67], v[126:127], off offset:3072
	global_load_dwordx4 v[68:71], v[126:127], off offset:3104
	global_load_dwordx4 v[72:75], v[126:127], off offset:3136
	global_load_dwordx4 v[76:79], v[126:127], off offset:3168
	global_load_dwordx4 v[80:83], v[126:127], off offset:3200
	global_load_dwordx4 v[84:87], v[126:127], off offset:3232
	global_load_dwordx4 v[88:91], v[126:127], off offset:3264
	global_load_dwordx4 v[92:95], v[126:127], off offset:3296
	global_load_dwordx4 v[98:101], v[126:127], off offset:3328
	global_load_dwordx4 v[102:105], v[126:127], off offset:3360
	global_load_dwordx4 v[106:109], v[126:127], off offset:3392
	global_load_dwordx4 v[110:113], v[126:127], off offset:3424
	global_load_dwordx4 v[114:117], v[126:127], off offset:3456
	global_load_dwordx4 v[118:121], v[126:127], off offset:3488
	global_load_dwordx4 v[122:125], v[126:127], off offset:3520
	s_nop 0
	global_load_dwordx4 v[126:129], v[126:127], off offset:3552
	v_lshlrev_b32_e32 v130, 13, v140
	v_mov_b32_e32 v131, v163
	v_lshl_add_u64 v[130:131], s[86:87], 0, v[130:131]
	s_waitcnt vmcnt(15)
	v_mul_f32_e32 v48, v48, v64
	v_mul_f32_e32 v49, v49, v65
	v_cvt_pk_bf16_f32 v64, v48, v49
	v_mul_f32_e32 v48, v50, v66
	v_mul_f32_e32 v49, v51, v67
	v_cvt_pk_bf16_f32 v65, v48, v49
	v_lshlrev_b32_e32 v48, 3, v139
	v_lshl_or_b32 v48, v138, 8, v48
	v_mov_b32_e32 v49, v163
	v_lshl_add_u64 v[50:51], v[130:131], 0, v[48:49]
	s_mov_b64 s[12:13], 0x22900600
	v_lshl_add_u64 v[48:49], v[50:51], 0, s[12:13]
	s_mov_b32 s12, 0x22900000
	s_waitcnt vmcnt(11)
	v_mul_f32_e32 v32, v32, v80
	v_mul_f32_e32 v33, v33, v81
	s_waitcnt vmcnt(7)
	v_mul_f32_e32 v16, v16, v98
	v_mul_f32_e32 v17, v17, v99
	s_waitcnt vmcnt(3)
	v_mul_f32_e32 v0, v0, v114
	v_mul_f32_e32 v1, v1, v115
	v_add_co_u32_e32 v50, vcc, s12, v50
	v_cvt_pk_bf16_f32 v32, v32, v33
	v_mul_f32_e32 v33, v34, v82
	v_cvt_pk_bf16_f32 v16, v16, v17
	v_mul_f32_e32 v17, v18, v100
	v_cvt_pk_bf16_f32 v0, v0, v1
	v_mul_f32_e32 v1, v2, v116
	v_addc_co_u32_e32 v51, vcc, 0, v51, vcc
	v_mul_f32_e32 v34, v35, v83
	v_cvt_pk_bf16_f32 v33, v33, v34
	v_mul_f32_e32 v18, v19, v101
	v_cvt_pk_bf16_f32 v17, v17, v18
	v_mul_f32_e32 v2, v3, v117
	v_cvt_pk_bf16_f32 v1, v1, v2
	global_store_dwordx2 v[50:51], v[64:65], off offset:1536
	v_mul_f32_e32 v50, v52, v68
	v_mul_f32_e32 v51, v53, v69
	global_store_dwordx2 v[48:49], v[32:33], off offset:64
	v_mul_f32_e32 v32, v36, v84
	v_mul_f32_e32 v33, v37, v85
	global_store_dwordx2 v[48:49], v[16:17], off offset:128
	v_mul_f32_e32 v16, v20, v102
	v_mul_f32_e32 v17, v21, v103
	global_store_dwordx2 v[48:49], v[0:1], off offset:192
	s_waitcnt vmcnt(6)
	v_mul_f32_e32 v0, v4, v118
	v_mul_f32_e32 v1, v5, v119
	v_cvt_pk_bf16_f32 v50, v50, v51
	v_mul_f32_e32 v51, v54, v70
	v_cvt_pk_bf16_f32 v32, v32, v33
	v_mul_f32_e32 v33, v38, v86
	v_cvt_pk_bf16_f32 v16, v16, v17
	v_mul_f32_e32 v17, v22, v104
	v_cvt_pk_bf16_f32 v0, v0, v1
	v_mul_f32_e32 v1, v6, v120
	v_mul_f32_e32 v52, v55, v71
	v_cvt_pk_bf16_f32 v51, v51, v52
	v_mul_f32_e32 v34, v39, v87
	v_cvt_pk_bf16_f32 v33, v33, v34
	v_mul_f32_e32 v18, v23, v105
	v_cvt_pk_bf16_f32 v17, v17, v18
	v_mul_f32_e32 v2, v7, v121
	v_cvt_pk_bf16_f32 v1, v1, v2
	global_store_dwordx2 v[48:49], v[50:51], off offset:16
	v_mul_f32_e32 v50, v56, v72
	v_mul_f32_e32 v51, v57, v73
	global_store_dwordx2 v[48:49], v[32:33], off offset:80
	v_mul_f32_e32 v32, v40, v88
	v_mul_f32_e32 v33, v41, v89
	global_store_dwordx2 v[48:49], v[16:17], off offset:144
	v_mul_f32_e32 v16, v24, v106
	v_mul_f32_e32 v17, v25, v107
	global_store_dwordx2 v[48:49], v[0:1], off offset:208
	s_waitcnt vmcnt(9)
	v_mul_f32_e32 v0, v8, v122
	v_mul_f32_e32 v1, v9, v123
	v_cvt_pk_bf16_f32 v50, v50, v51
	v_mul_f32_e32 v51, v58, v74
	v_cvt_pk_bf16_f32 v32, v32, v33
	v_mul_f32_e32 v33, v42, v90
	v_cvt_pk_bf16_f32 v16, v16, v17
	v_mul_f32_e32 v17, v26, v108
	v_cvt_pk_bf16_f32 v0, v0, v1
	v_mul_f32_e32 v1, v10, v124
	v_mul_f32_e32 v52, v59, v75
	v_cvt_pk_bf16_f32 v51, v51, v52
	v_mul_f32_e32 v34, v43, v91
	v_cvt_pk_bf16_f32 v33, v33, v34
	v_mul_f32_e32 v18, v27, v109
	v_cvt_pk_bf16_f32 v17, v17, v18
	v_mul_f32_e32 v2, v11, v125
	v_cvt_pk_bf16_f32 v1, v1, v2
	global_store_dwordx2 v[48:49], v[50:51], off offset:32
	v_mul_f32_e32 v50, v60, v76
	v_mul_f32_e32 v51, v61, v77
	global_store_dwordx2 v[48:49], v[32:33], off offset:96
	v_mul_f32_e32 v32, v44, v92
	v_mul_f32_e32 v33, v45, v93
	global_store_dwordx2 v[48:49], v[16:17], off offset:160
	v_mul_f32_e32 v16, v28, v110
	v_mul_f32_e32 v17, v29, v111
	global_store_dwordx2 v[48:49], v[0:1], off offset:224
	s_waitcnt vmcnt(12)
	v_mul_f32_e32 v0, v12, v126
	v_mul_f32_e32 v1, v13, v127
	v_cvt_pk_bf16_f32 v50, v50, v51
	v_mul_f32_e32 v51, v62, v78
	v_cvt_pk_bf16_f32 v32, v32, v33
	v_mul_f32_e32 v33, v46, v94
	v_cvt_pk_bf16_f32 v16, v16, v17
	v_mul_f32_e32 v17, v30, v112
	v_cvt_pk_bf16_f32 v0, v0, v1
	v_mul_f32_e32 v1, v14, v128
	s_andn2_b64 s[8:9], s[8:9], exec
	v_mul_f32_e32 v52, v63, v79
	v_cvt_pk_bf16_f32 v51, v51, v52
	global_store_dwordx2 v[48:49], v[50:51], off offset:48
	v_mul_f32_e32 v34, v47, v95
	v_cvt_pk_bf16_f32 v33, v33, v34
	global_store_dwordx2 v[48:49], v[32:33], off offset:112
	v_mul_f32_e32 v18, v31, v113
	v_cvt_pk_bf16_f32 v17, v17, v18
	global_store_dwordx2 v[48:49], v[16:17], off offset:176
	v_mul_f32_e32 v2, v15, v129
	v_cvt_pk_bf16_f32 v1, v1, v2
	s_or_b64 exec, exec, s[10:11]
	s_and_saveexec_b64 s[10:11], s[8:9]
	s_xor_b64 s[8:9], exec, s[10:11]
	s_cbranch_execz .LBB0_190
